# v58 + pooling mixer: the 16 halo rows of the next 32-row item are copied from the current item's registers instead of being re-loaded (grouped mode only; 8 instead of 12 tile loads per item)
# speedup vs baseline: 1.0044x; 1.0044x over previous
; #define LAS __attribute__((address_space(3)))
; #define LDS_WAIT() asm volatile("s_waitcnt lgkmcnt(0)" ::: "memory")
; #define lane (hw_lane())
; __device__ __forceinline__ void pool_load(const bf16* proj, int it, int lane, v4u (&raw)[12]) {
;     const int chunk = it >> 4, g = (it >> 2) & 3, rq = it & 3; proj += (size_t)(chunk >> 6) * GAP_P;
;     const size_t R0 = (size_t)chunk * 128 + rq * 32; const int tseq = (int)(R0 & (SEQ - 1)), r = lane & 15, q = lane >> 4;
; #pragma unroll
;     for (int i = 0; i < 12; ++i) { const int row = q + 4 * i; raw[i] = (v4u){0u, 0u, 0u, 0u};
;         if (row >= 16 || tseq != 0) raw[i] = __builtin_nontemporal_load((const v4u*)(proj + (R0 + row - 16) * DIN + g * 128 + r * 8)); }
; }
; __device__ __forceinline__ void pool_item(LAS unsigned char* wl, const bf16* proj, bf16* ymix, const bf16* WpT, const float* pscale, int chunk, int g, int rq, int lane, v4u (&raw)[12], int nxt_it) {
;     ymix += (size_t)(chunk >> 6) * GAP_Y;
;     const size_t R0 = (size_t)chunk * 128 + rq * 32; const int tseq = (int)(R0 & (SEQ - 1));
;     const int r = lane & 15, q = lane >> 4, win = 2 << g;
; #pragma unroll
;     for (int i = 0; i < 12; ++i) *(LAS v4u*)(wl + (q + 4 * i) * PP + r * 16) = raw[i];
;     LDS_WAIT();
;     if (nxt_it >= 0) pool_load(proj, nxt_it, lane, raw);
.LBB0_500:
	s_add_i32 s15, s22, s77
	v_readlane_b32 s4, v254, 41
	s_cmp_ge_i32 s15, s4
	s_waitcnt vmcnt(8) lgkmcnt(0)
	ds_write_b128 v99, v[0:3]
	ds_write_b128 v99, v[4:7] offset:1088
	ds_write_b128 v99, v[8:11] offset:2176
	ds_write_b128 v101, v[12:15]
	ds_write_b128 v99, v[40:43] offset:4352
	ds_write_b128 v99, v[44:47] offset:5440
	ds_write_b128 v99, v[24:27] offset:6528
	ds_write_b128 v99, v[28:31] offset:7616
	ds_write_b128 v99, v[32:35] offset:8704
	ds_write_b128 v99, v[36:39] offset:9792
	ds_write_b128 v99, v[16:19] offset:10880
	ds_write_b128 v99, v[20:23] offset:11968
	s_cselect_b64 s[0:1], -1, 0
	s_cmp_lt_i32 s15, s4
	s_waitcnt lgkmcnt(0)
	s_cselect_b32 s23, s15, -1
	s_cmp_lt_i32 s23, 0
	s_cbranch_scc1 .LBB0_505
	s_lshr_b32 s4, s23, 10
	s_lshr_b32 s86, s23, 4
	s_mul_hi_u32 s5, s4, 0x1400000
	s_mul_i32 s4, s4, 0x1400000
	s_add_u32 s10, s9, s4
	s_addc_u32 s11, s12, s5
	s_lshl_b32 s23, s23, 5
	s_lshl_b64 s[4:5], s[86:87], 7
	s_and_b32 s6, s23, 0x60
	s_or_b32 s4, s4, s6
	s_and_b32 s86, s4, 0x1fe0
	s_and_b32 s23, s23, 0x180
	s_cmp_eq_u64 s[86:87], 0
	s_cbranch_scc1 .LBB0_503
	s_cmp_lg_u32 s77, 1
	s_cbranch_scc1 .Lpool_halo_ld
	v_mov_b32_e32 v0, v32
	v_mov_b32_e32 v1, v33
	v_mov_b32_e32 v2, v34
	v_mov_b32_e32 v3, v35
	v_mov_b32_e32 v4, v36
	v_mov_b32_e32 v5, v37
	v_mov_b32_e32 v6, v38
	v_mov_b32_e32 v7, v39
	v_mov_b32_e32 v8, v16
	v_mov_b32_e32 v9, v17
	v_mov_b32_e32 v10, v18
	v_mov_b32_e32 v11, v19
	v_mov_b32_e32 v12, v20
	v_mov_b32_e32 v13, v21
	v_mov_b32_e32 v14, v22
	v_mov_b32_e32 v15, v23
	s_branch .LBB0_504
.Lpool_halo_ld:
	v_or_b32_e32 v0, s4, v80
	v_mov_b64_e32 v[8:9], s[10:11]
	v_mad_u64_u32 v[0:1], s[24:25], v0, s7, v[8:9]
	v_mad_u32_u24 v1, s5, v242, v1
	s_lshl_b32 s86, s23, 1
	v_or_b32_e32 v2, s4, v102
	v_lshl_add_u64 v[0:1], v[0:1], 0, s[86:87]
	v_mad_u64_u32 v[2:3], s[24:25], v2, s7, v[8:9]
	v_lshl_add_u64 v[0:1], v[0:1], 0, v[192:193]
	v_mad_u32_u24 v3, s5, v242, v3
	v_or_b32_e32 v10, s4, v82
	v_or_b32_e32 v12, s4, v84
	v_add_co_u32_e32 v0, vcc, s83, v0
	v_lshl_add_u64 v[2:3], v[2:3], 0, s[86:87]
	v_mad_u64_u32 v[10:11], s[24:25], v10, s7, v[8:9]
	v_mad_u64_u32 v[8:9], s[24:25], v12, s7, v[8:9]
	v_addc_co_u32_e32 v1, vcc, -1, v1, vcc
	v_lshl_add_u64 v[2:3], v[2:3], 0, v[192:193]
	v_mad_u32_u24 v11, s5, v242, v11
	v_or_b32_e32 v13, s5, v85
	v_mov_b32_e32 v12, v9
	v_add_co_u32_e32 v4, vcc, s83, v2
	v_lshl_add_u64 v[10:11], v[10:11], 0, s[86:87]
	v_mad_u64_u32 v[12:13], s[24:25], v13, s7, v[12:13]
	v_addc_co_u32_e32 v5, vcc, -1, v3, vcc
	v_lshl_add_u64 v[10:11], v[10:11], 0, v[192:193]
	v_mov_b32_e32 v9, v12
	v_add_co_u32_e32 v10, vcc, s83, v10
	v_lshl_add_u64 v[8:9], v[8:9], 0, s[86:87]
	s_nop 0
	v_addc_co_u32_e32 v11, vcc, -1, v11, vcc
	v_lshl_add_u64 v[8:9], v[8:9], 0, v[192:193]
	v_add_co_u32_e32 v12, vcc, 0xffff4000, v8
	global_load_dwordx4 v[0:3], v[0:1], off nt
	s_nop 0
	global_load_dwordx4 v[4:7], v[4:5], off nt
	v_addc_co_u32_e32 v13, vcc, -1, v9, vcc
	global_load_dwordx4 v[8:11], v[10:11], off nt
	s_nop 0
	global_load_dwordx4 v[12:15], v[12:13], off nt
	s_branch .LBB0_504
